# K-loop rotation (next-step LDS-DMA issued between MFMAs, SGPR-base addressing) also applied to HYB in-proj and residual GEMM main loops
# speedup vs baseline: 1.2158x; 1.0042x over previous
;     ...
;     f32x4 acc[MI][4];
; #pragma unroll
;     for (int i = 0; i < MI; i++)
; #pragma unroll
;       for (int j = 0; j < 4; j++) acc[i][j] = (f32x4){0.f, 0.f, 0.f, 0.f};
;     ...
;       const bf16_t* ap = A + (size_t)(m0 + lrow) * lda + lsw;
;       const bf16_t* bp = Wt + (size_t)(n0 + lrow) * K + lsw;
;       const size_t a32 = (size_t)32 * lda, b32 = (size_t)32 * K;
;       typedef __attribute__((address_space(3))) unsigned lds_u32;
;       lds_u32* sbase = (lds_u32*)(smem) + wave * 256;
;       for (int kt = 0; kt < KT; kt++) {
;         {
;           const bf16_t* apx = ap;
;           int kc = kt * 64;
;           if (SHIFT && kc >= 1024) { apx = ap - lda; kc -= 1024; }
; #pragma unroll
;           for (int i = 0; i < 8; i++)
;             __builtin_amdgcn_global_load_lds((const unsigned*)(apx + i * a32 + kc), sbase + i * 1024, 16, 0, 0);
; #pragma unroll
;           for (int i = 0; i < 4; i++)
;             __builtin_amdgcn_global_load_lds((const unsigned*)(bp + i * b32 + kt * 64), sbase + 8192 + i * 1024, 16, 0, 0);
.LBB0_2194:
	s_lshl_b32 s7, s9, 8
	v_add_u32_e32 v10, s7, v150
	v_ashrrev_i32_e32 v11, 31, v10
	s_lshl_b32 s9, s6, 7
	v_lshlrev_b64 v[10:11], 11, v[10:11]
	v_lshl_add_u64 v[146:147], v[142:143], 0, v[10:11]
	v_add_u32_e32 v10, s9, v150
	v_ashrrev_i32_e32 v11, 31, v10
	v_lshlrev_b64 v[10:11], 11, v[10:11]
	v_lshl_add_u64 v[148:149], v[144:145], 0, v[10:11]
	v_mov_b32_e32 v10, 0
	s_mov_b64 s[4:5], 0
	v_mov_b32_e32 v11, v10
	v_mov_b32_e32 v12, v10
	v_mov_b32_e32 v13, v10
	v_mov_b32_e32 v14, v10
	v_mov_b32_e32 v15, v10
	v_mov_b32_e32 v16, v10
	v_mov_b32_e32 v17, v10
	v_mov_b32_e32 v18, v10
	v_mov_b32_e32 v19, v10
	v_mov_b32_e32 v20, v10
	v_mov_b32_e32 v21, v10
	v_mov_b32_e32 v22, v10
	v_mov_b32_e32 v23, v10
	v_mov_b32_e32 v24, v10
	v_mov_b32_e32 v25, v10
	v_mov_b32_e32 v26, v10
	v_mov_b32_e32 v27, v10
	v_mov_b32_e32 v28, v10
	v_mov_b32_e32 v29, v10
	v_mov_b32_e32 v30, v10
	v_mov_b32_e32 v31, v10
	v_mov_b32_e32 v32, v10
	v_mov_b32_e32 v33, v10
	v_mov_b32_e32 v34, v10
	v_mov_b32_e32 v35, v10
	v_mov_b32_e32 v36, v10
	v_mov_b32_e32 v37, v10
	v_mov_b32_e32 v38, v10
	v_mov_b32_e32 v39, v10
	v_mov_b32_e32 v40, v10
	v_mov_b32_e32 v41, v10
	v_mov_b32_e32 v42, v10
	v_mov_b32_e32 v43, v10
	v_mov_b32_e32 v44, v10
	v_mov_b32_e32 v45, v10
	v_mov_b32_e32 v46, v10
	v_mov_b32_e32 v47, v10
	v_mov_b32_e32 v48, v10
	v_mov_b32_e32 v49, v10
	v_mov_b32_e32 v50, v10
	v_mov_b32_e32 v51, v10
	v_mov_b32_e32 v52, v10
	v_mov_b32_e32 v53, v10
	v_mov_b32_e32 v54, v10
	v_mov_b32_e32 v55, v10
	v_mov_b32_e32 v56, v10
	v_mov_b32_e32 v57, v10
	v_mov_b32_e32 v58, v10
	v_mov_b32_e32 v59, v10
	v_mov_b32_e32 v60, v10
	v_mov_b32_e32 v61, v10
	v_mov_b32_e32 v62, v10
	v_mov_b32_e32 v63, v10
	v_mov_b32_e32 v64, v10
	v_mov_b32_e32 v65, v10
	v_mov_b32_e32 v66, v10
	v_mov_b32_e32 v67, v10
	v_mov_b32_e32 v68, v10
	v_mov_b32_e32 v69, v10
	v_mov_b32_e32 v70, v10
	v_mov_b32_e32 v71, v10
	v_mov_b32_e32 v72, v10
	v_mov_b32_e32 v73, v10
	v_mov_b32_e32 v74, v10
	v_mov_b32_e32 v75, v10
	v_mov_b32_e32 v76, v10
	v_mov_b32_e32 v77, v10
	v_mov_b32_e32 v78, v10
	v_mov_b32_e32 v79, v10
	v_mov_b32_e32 v80, v10
	v_mov_b32_e32 v81, v10
	v_mov_b32_e32 v82, v10
	v_mov_b32_e32 v83, v10
	v_mov_b32_e32 v84, v10
	v_mov_b32_e32 v85, v10
	v_mov_b32_e32 v86, v10
	v_mov_b32_e32 v87, v10
	v_mov_b32_e32 v88, v10
	v_mov_b32_e32 v89, v10
	v_mov_b32_e32 v90, v10
	v_mov_b32_e32 v91, v10
	v_mov_b32_e32 v92, v10
	v_mov_b32_e32 v93, v10
	v_mov_b32_e32 v94, v10
	v_mov_b32_e32 v95, v10
	v_mov_b32_e32 v96, v10
	v_mov_b32_e32 v97, v10
	v_mov_b32_e32 v98, v10
	v_mov_b32_e32 v99, v10
	v_mov_b32_e32 v100, v10
	v_mov_b32_e32 v101, v10
	v_mov_b32_e32 v102, v10
	v_mov_b32_e32 v103, v10
	v_mov_b32_e32 v104, v10
	v_mov_b32_e32 v105, v10
	v_mov_b32_e32 v106, v10
	v_mov_b32_e32 v107, v10
	v_mov_b32_e32 v108, v10
	v_mov_b32_e32 v109, v10
	v_mov_b32_e32 v110, v10
	v_mov_b32_e32 v111, v10
	v_mov_b32_e32 v112, v10
	v_mov_b32_e32 v113, v10
	v_mov_b32_e32 v114, v10
	v_mov_b32_e32 v115, v10
	v_mov_b32_e32 v116, v10
	v_mov_b32_e32 v117, v10
	v_mov_b32_e32 v118, v10
	v_mov_b32_e32 v119, v10
	v_mov_b32_e32 v120, v10
	v_mov_b32_e32 v121, v10
	v_mov_b32_e32 v122, v10
	v_mov_b32_e32 v123, v10
	v_mov_b32_e32 v124, v10
	v_mov_b32_e32 v125, v10
	v_mov_b32_e32 v126, v10
	v_mov_b32_e32 v127, v10
	v_mov_b32_e32 v128, v10
	v_mov_b32_e32 v129, v10
	v_mov_b32_e32 v130, v10
	v_mov_b32_e32 v131, v10
	v_mov_b32_e32 v132, v10
	v_mov_b32_e32 v133, v10
	v_mov_b32_e32 v134, v10
	v_mov_b32_e32 v135, v10
	v_mov_b32_e32 v136, v10
	v_mov_b32_e32 v137, v10
	v_lshrrev_b32_e32 v243, 3, v2
	v_and_b32_e32 v243, 7, v243
	v_lshrrev_b32_e32 v240, 4, v2
	v_xor_b32_e32 v240, v240, v2
	v_and_b32_e32 v240, 7, v240
	v_lshlrev_b32_e32 v240, 4, v240
	v_mov_b32_e32 v241, 0x800
	v_mad_u32_u24 v242, v243, v241, v240
	v_sub_co_u32_e32 v240, vcc, v146, v242
	s_nop 1
	v_subbrev_co_u32_e32 v241, vcc, 0, v147, vcc
	v_readfirstlane_b32 s10, v152
	v_readfirstlane_b32 s100, v240
	v_readfirstlane_b32 s101, v241
	s_add_u32 s12, s100, 0x800
	s_addc_u32 s13, s101, 0
	s_add_u32 s14, s100, 0x10800
	s_addc_u32 s15, s101, 0
	s_add_u32 s16, s100, 0x20800
	s_addc_u32 s17, s101, 0
	s_add_u32 s18, s100, 0x30800
	s_addc_u32 s19, s101, 0
	s_add_u32 s20, s100, 0x40800
	s_addc_u32 s21, s101, 0
	s_add_u32 s22, s100, 0x50800
	s_addc_u32 s23, s101, 0
	s_add_u32 s24, s100, 0x60800
	s_addc_u32 s25, s101, 0
	s_add_u32 s26, s100, 0x70800
	s_addc_u32 s27, s101, 0
	s_mov_b64 s[100:101], 0xa300000
	v_lshl_add_u64 v[234:235], v[148:149], 0, s[100:101]
	s_mov_b64 s[100:101], 0xa310000
	v_lshl_add_u64 v[236:237], v[148:149], 0, s[100:101]
	s_mov_b64 s[100:101], 0xa320000
	v_lshl_add_u64 v[238:239], v[148:149], 0, s[100:101]
	s_mov_b64 s[100:101], 0xa330000
	v_lshl_add_u64 v[240:241], v[148:149], 0, s[100:101]
	s_mov_b64 s[100:101], 0x80
	s_mov_b32 m0, s10
	s_nop 0
	global_load_lds_dwordx4 v242, s[12:13]
	s_add_u32 m0, s10, 0x1000
	s_nop 0
	global_load_lds_dwordx4 v242, s[14:15]
	s_add_u32 m0, s10, 0x2000
	s_nop 0
	global_load_lds_dwordx4 v242, s[16:17]
	s_add_u32 m0, s10, 0x3000
	s_nop 0
	global_load_lds_dwordx4 v242, s[18:19]
	s_add_u32 m0, s10, 0x4000
	s_nop 0
	global_load_lds_dwordx4 v242, s[20:21]
	s_add_u32 m0, s10, 0x5000
	s_nop 0
	global_load_lds_dwordx4 v242, s[22:23]
	s_add_u32 m0, s10, 0x6000
	s_nop 0
	global_load_lds_dwordx4 v242, s[24:25]
	s_add_u32 m0, s10, 0x7000
	s_nop 0
	global_load_lds_dwordx4 v242, s[26:27]
	s_add_u32 m0, s10, 0x8000
	s_nop 0
	global_load_lds_dwordx4 v[234:235], off
	s_add_u32 m0, s10, 0x9000
	s_nop 0
	global_load_lds_dwordx4 v[236:237], off
	s_add_u32 m0, s10, 0xa000
	s_nop 0
	global_load_lds_dwordx4 v[238:239], off
	s_add_u32 m0, s10, 0xb000
	s_nop 0
	global_load_lds_dwordx4 v[240:241], off
;     ...
;       for (int kt = 0; kt < KT; kt++) {
;         {
;           const bf16_t* apx = ap;
;           int kc = kt * 64;
;           if (SHIFT && kc >= 1024) { apx = ap - lda; kc -= 1024; }
; #pragma unroll
;           for (int i = 0; i < 8; i++)
;             __builtin_amdgcn_global_load_lds((const unsigned*)(apx + i * a32 + kc), sbase + i * 1024, 16, 0, 0);
; #pragma unroll
;           for (int i = 0; i < 4; i++)
;             __builtin_amdgcn_global_load_lds((const unsigned*)(bp + i * b32 + kt * 64), sbase + 8192 + i * 1024, 16, 0, 0);
;         }
;         asm volatile("s_waitcnt vmcnt(0)" ::: "memory");
;         __syncthreads();
; #pragma unroll
;         for (int kk = 0; kk < 2; kk++) {
;           bf16x8 af[MI], bfr[4];
;           const int csw = (((kk * 4 + fq) ^ fsw) << 3);
; #pragma unroll
;           for (int mi = 0; mi < MI; mi++) af[mi] = *(const bf16x8*)(smem + (wm * 128 + mi * 16 + fr) * 64 + csw);
; #pragma unroll
;           for (int ni = 0; ni < 4; ni++) bfr[ni] = *(const bf16x8*)(smem + 16384 + (wn * 64 + ni * 16 + fr) * 64 + csw);
; #pragma unroll
;           for (int mi = 0; mi < MI; mi++)
; #pragma unroll
;             for (int ni = 0; ni < 4; ni++)
;               acc[mi][ni] = __builtin_amdgcn_mfma_f32_16x16x32_bf16(bfr[ni], af[mi], acc[mi][ni], 0, 0, 0);
.Lhy_loop:
	s_waitcnt vmcnt(0)
	s_barrier
	v_add_u32_e32 v8, v156, v157
	ds_read_b128 v[170:173], v8
	ds_read_b128 v[174:177], v8 offset:2048
	ds_read_b128 v[178:181], v8 offset:4096
	ds_read_b128 v[182:185], v8 offset:6144
	ds_read_b128 v[186:189], v8 offset:8192
	ds_read_b128 v[190:193], v8 offset:10240
	ds_read_b128 v[194:197], v8 offset:12288
	ds_read_b128 v[138:141], v8 offset:14336
	ds_read_b128 v[198:201], v168 offset:32768
	ds_read_b128 v[202:205], v168 offset:34816
	ds_read_b128 v[226:229], v168 offset:36864
	ds_read_b128 v[230:233], v168 offset:38912
	v_add_u32_e32 v8, v158, v157
	s_waitcnt lgkmcnt(3)
	v_mfma_f32_16x16x32_bf16 v[134:137], v[198:201], v[170:173], v[134:137]
	s_add_u32 s4, s4, 0x80
	s_addc_u32 s5, s5, 0
	s_cmpk_eq_i32 s4, 0x800
	s_waitcnt lgkmcnt(2)
	v_mfma_f32_16x16x32_bf16 v[130:133], v[202:205], v[170:173], v[130:133]
	s_waitcnt lgkmcnt(1)
	v_mfma_f32_16x16x32_bf16 v[126:129], v[226:229], v[170:173], v[126:129]
	s_waitcnt lgkmcnt(0)
	v_mfma_f32_16x16x32_bf16 v[122:125], v[230:233], v[170:173], v[122:125]
	v_mfma_f32_16x16x32_bf16 v[118:121], v[198:201], v[174:177], v[118:121]
	v_mfma_f32_16x16x32_bf16 v[114:117], v[202:205], v[174:177], v[114:117]
	v_mfma_f32_16x16x32_bf16 v[110:113], v[226:229], v[174:177], v[110:113]
	v_mfma_f32_16x16x32_bf16 v[106:109], v[230:233], v[174:177], v[106:109]
	v_mfma_f32_16x16x32_bf16 v[102:105], v[198:201], v[178:181], v[102:105]
	v_mfma_f32_16x16x32_bf16 v[98:101], v[202:205], v[178:181], v[98:101]
	v_mfma_f32_16x16x32_bf16 v[94:97], v[226:229], v[178:181], v[94:97]
	v_mfma_f32_16x16x32_bf16 v[90:93], v[230:233], v[178:181], v[90:93]
	v_mfma_f32_16x16x32_bf16 v[86:89], v[198:201], v[182:185], v[86:89]
	v_mfma_f32_16x16x32_bf16 v[82:85], v[202:205], v[182:185], v[82:85]
	v_mfma_f32_16x16x32_bf16 v[78:81], v[226:229], v[182:185], v[78:81]
	v_mfma_f32_16x16x32_bf16 v[74:77], v[230:233], v[182:185], v[74:77]
	v_mfma_f32_16x16x32_bf16 v[70:73], v[198:201], v[186:189], v[70:73]
	v_mfma_f32_16x16x32_bf16 v[66:69], v[202:205], v[186:189], v[66:69]
	v_mfma_f32_16x16x32_bf16 v[62:65], v[226:229], v[186:189], v[62:65]
	v_mfma_f32_16x16x32_bf16 v[58:61], v[230:233], v[186:189], v[58:61]
	v_mfma_f32_16x16x32_bf16 v[54:57], v[198:201], v[190:193], v[54:57]
	v_mfma_f32_16x16x32_bf16 v[50:53], v[202:205], v[190:193], v[50:53]
	v_mfma_f32_16x16x32_bf16 v[46:49], v[226:229], v[190:193], v[46:49]
	v_mfma_f32_16x16x32_bf16 v[42:45], v[230:233], v[190:193], v[42:45]
	v_mfma_f32_16x16x32_bf16 v[38:41], v[198:201], v[194:197], v[38:41]
	v_mfma_f32_16x16x32_bf16 v[34:37], v[202:205], v[194:197], v[34:37]
	v_mfma_f32_16x16x32_bf16 v[30:33], v[226:229], v[194:197], v[30:33]
	v_mfma_f32_16x16x32_bf16 v[26:29], v[230:233], v[194:197], v[26:29]
	v_mfma_f32_16x16x32_bf16 v[22:25], v[198:201], v[138:141], v[22:25]
	v_mfma_f32_16x16x32_bf16 v[18:21], v[202:205], v[138:141], v[18:21]
	v_mfma_f32_16x16x32_bf16 v[14:17], v[226:229], v[138:141], v[14:17]
	v_mfma_f32_16x16x32_bf16 v[10:13], v[230:233], v[138:141], v[10:13]
	ds_read_b128 v[138:141], v8
	ds_read_b128 v[170:173], v8 offset:2048
	ds_read_b128 v[174:177], v8 offset:4096
	ds_read_b128 v[178:181], v8 offset:6144
	ds_read_b128 v[182:185], v8 offset:8192
	ds_read_b128 v[186:189], v8 offset:10240
	ds_read_b128 v[190:193], v8 offset:12288
	ds_read_b128 v[194:197], v8 offset:14336
	ds_read_b128 v[198:201], v169 offset:32768
	ds_read_b128 v[202:205], v169 offset:34816
	ds_read_b128 v[226:229], v169 offset:36864
	ds_read_b128 v[230:233], v169 offset:38912
	s_waitcnt lgkmcnt(0)
	s_barrier
	s_cmpk_eq_i32 s4, 0x800
	s_cbranch_scc1 .Lhy_last
	v_add_u32_e32 v242, 0x80, v242
	v_lshl_add_u64 v[234:235], v[234:235], 0, s[100:101]
	v_lshl_add_u64 v[236:237], v[236:237], 0, s[100:101]
	v_lshl_add_u64 v[238:239], v[238:239], 0, s[100:101]
	v_lshl_add_u64 v[240:241], v[240:241], 0, s[100:101]
	v_mfma_f32_16x16x32_bf16 v[134:137], v[198:201], v[138:141], v[134:137]
	v_mfma_f32_16x16x32_bf16 v[130:133], v[202:205], v[138:141], v[130:133]
	v_mfma_f32_16x16x32_bf16 v[126:129], v[226:229], v[138:141], v[126:129]
	v_mfma_f32_16x16x32_bf16 v[122:125], v[230:233], v[138:141], v[122:125]
	v_mfma_f32_16x16x32_bf16 v[118:121], v[198:201], v[170:173], v[118:121]
	v_mfma_f32_16x16x32_bf16 v[114:117], v[202:205], v[170:173], v[114:117]
	s_mov_b32 m0, s10
	v_mfma_f32_16x16x32_bf16 v[110:113], v[226:229], v[170:173], v[110:113]
	global_load_lds_dwordx4 v242, s[12:13]
	v_mfma_f32_16x16x32_bf16 v[106:109], v[230:233], v[170:173], v[106:109]
	s_add_u32 m0, s10, 0x1000
	v_mfma_f32_16x16x32_bf16 v[102:105], v[198:201], v[174:177], v[102:105]
	global_load_lds_dwordx4 v242, s[14:15]
	v_mfma_f32_16x16x32_bf16 v[98:101], v[202:205], v[174:177], v[98:101]
	s_add_u32 m0, s10, 0x2000
	v_mfma_f32_16x16x32_bf16 v[94:97], v[226:229], v[174:177], v[94:97]
	global_load_lds_dwordx4 v242, s[16:17]
	v_mfma_f32_16x16x32_bf16 v[90:93], v[230:233], v[174:177], v[90:93]
	s_add_u32 m0, s10, 0x3000
	v_mfma_f32_16x16x32_bf16 v[86:89], v[198:201], v[178:181], v[86:89]
	global_load_lds_dwordx4 v242, s[18:19]
	v_mfma_f32_16x16x32_bf16 v[82:85], v[202:205], v[178:181], v[82:85]
	s_add_u32 m0, s10, 0x4000
	v_mfma_f32_16x16x32_bf16 v[78:81], v[226:229], v[178:181], v[78:81]
	global_load_lds_dwordx4 v242, s[20:21]
	v_mfma_f32_16x16x32_bf16 v[74:77], v[230:233], v[178:181], v[74:77]
	s_add_u32 m0, s10, 0x5000
	v_mfma_f32_16x16x32_bf16 v[70:73], v[198:201], v[182:185], v[70:73]
	global_load_lds_dwordx4 v242, s[22:23]
	v_mfma_f32_16x16x32_bf16 v[66:69], v[202:205], v[182:185], v[66:69]
	s_add_u32 m0, s10, 0x6000
	v_mfma_f32_16x16x32_bf16 v[62:65], v[226:229], v[182:185], v[62:65]
	global_load_lds_dwordx4 v242, s[24:25]
	v_mfma_f32_16x16x32_bf16 v[58:61], v[230:233], v[182:185], v[58:61]
	s_add_u32 m0, s10, 0x7000
	v_mfma_f32_16x16x32_bf16 v[54:57], v[198:201], v[186:189], v[54:57]
	global_load_lds_dwordx4 v242, s[26:27]
	v_mfma_f32_16x16x32_bf16 v[50:53], v[202:205], v[186:189], v[50:53]
	s_add_u32 m0, s10, 0x8000
	v_mfma_f32_16x16x32_bf16 v[46:49], v[226:229], v[186:189], v[46:49]
	global_load_lds_dwordx4 v[234:235], off
	v_mfma_f32_16x16x32_bf16 v[42:45], v[230:233], v[186:189], v[42:45]
	s_add_u32 m0, s10, 0x9000
	v_mfma_f32_16x16x32_bf16 v[38:41], v[198:201], v[190:193], v[38:41]
	global_load_lds_dwordx4 v[236:237], off
	v_mfma_f32_16x16x32_bf16 v[34:37], v[202:205], v[190:193], v[34:37]
	s_add_u32 m0, s10, 0xa000
	v_mfma_f32_16x16x32_bf16 v[30:33], v[226:229], v[190:193], v[30:33]
	global_load_lds_dwordx4 v[238:239], off
	v_mfma_f32_16x16x32_bf16 v[26:29], v[230:233], v[190:193], v[26:29]
	s_add_u32 m0, s10, 0xb000
	v_mfma_f32_16x16x32_bf16 v[22:25], v[198:201], v[194:197], v[22:25]
	global_load_lds_dwordx4 v[240:241], off
	v_mfma_f32_16x16x32_bf16 v[18:21], v[202:205], v[194:197], v[18:21]
	v_mfma_f32_16x16x32_bf16 v[14:17], v[226:229], v[194:197], v[14:17]
	v_mfma_f32_16x16x32_bf16 v[10:13], v[230:233], v[194:197], v[10:13]
	s_branch .Lhy_loop
;     ...
;           for (int mi = 0; mi < MI; mi++)
; #pragma unroll
;             for (int ni = 0; ni < 4; ni++)
;               acc[mi][ni] = __builtin_amdgcn_mfma_f32_16x16x32_bf16(bfr[ni], af[mi], acc[mi][ni], 0, 0, 0);
;     ...
;             } else if constexpr (EPI == EPI_HYB) {
;               if (col >= 1024 && col < 1536) {
;                 const unsigned bb = row / (unsigned)LP;
;                 const unsigned vb_ = ((bb * 8u + ((col - 1024) >> 6)) * 64u + (col & 63)) * (unsigned)LP + (row - bb * (unsigned)LP);
;                 e.b1[vb_] = f2bf(a[0]); e.b1[vb_ + LP] = f2bf(a[1]); e.b1[vb_ + 2 * LP] = f2bf(a[2]); e.b1[vb_ + 3 * LP] = f2bf(a[3]);
;               } else if (col < ZLD) {
;                 uint2 o; o.x = pack2(a[0], a[1]); o.y = pack2(a[2], a[3]);
;                 *(uint2*)(e.b0 + (row * (unsigned)ZLD + col)) = o;
;               } else if (col < ZLD + 16) {
;                 *(float4*)(e.f0 + (row * 16u + (col - ZLD))) = make_float4(a[0], a[1], a[2], a[3]);
;               }
.Lhy_last:
	v_mfma_f32_16x16x32_bf16 v[134:137], v[198:201], v[138:141], v[134:137]
	v_mfma_f32_16x16x32_bf16 v[130:133], v[202:205], v[138:141], v[130:133]
	v_mfma_f32_16x16x32_bf16 v[126:129], v[226:229], v[138:141], v[126:129]
	v_mfma_f32_16x16x32_bf16 v[122:125], v[230:233], v[138:141], v[122:125]
	v_mfma_f32_16x16x32_bf16 v[118:121], v[198:201], v[170:173], v[118:121]
	v_mfma_f32_16x16x32_bf16 v[114:117], v[202:205], v[170:173], v[114:117]
	v_mfma_f32_16x16x32_bf16 v[110:113], v[226:229], v[170:173], v[110:113]
	v_mfma_f32_16x16x32_bf16 v[106:109], v[230:233], v[170:173], v[106:109]
	v_mfma_f32_16x16x32_bf16 v[102:105], v[198:201], v[174:177], v[102:105]
	v_mfma_f32_16x16x32_bf16 v[98:101], v[202:205], v[174:177], v[98:101]
	v_mfma_f32_16x16x32_bf16 v[94:97], v[226:229], v[174:177], v[94:97]
	v_mfma_f32_16x16x32_bf16 v[90:93], v[230:233], v[174:177], v[90:93]
	v_mfma_f32_16x16x32_bf16 v[86:89], v[198:201], v[178:181], v[86:89]
	v_mfma_f32_16x16x32_bf16 v[82:85], v[202:205], v[178:181], v[82:85]
	v_mfma_f32_16x16x32_bf16 v[78:81], v[226:229], v[178:181], v[78:81]
	v_mfma_f32_16x16x32_bf16 v[74:77], v[230:233], v[178:181], v[74:77]
	v_mfma_f32_16x16x32_bf16 v[70:73], v[198:201], v[182:185], v[70:73]
	v_mfma_f32_16x16x32_bf16 v[66:69], v[202:205], v[182:185], v[66:69]
	v_mfma_f32_16x16x32_bf16 v[62:65], v[226:229], v[182:185], v[62:65]
	v_mfma_f32_16x16x32_bf16 v[58:61], v[230:233], v[182:185], v[58:61]
	v_mfma_f32_16x16x32_bf16 v[54:57], v[198:201], v[186:189], v[54:57]
	v_mfma_f32_16x16x32_bf16 v[50:53], v[202:205], v[186:189], v[50:53]
	v_mfma_f32_16x16x32_bf16 v[46:49], v[226:229], v[186:189], v[46:49]
	v_mfma_f32_16x16x32_bf16 v[42:45], v[230:233], v[186:189], v[42:45]
	v_mfma_f32_16x16x32_bf16 v[38:41], v[198:201], v[190:193], v[38:41]
	v_mfma_f32_16x16x32_bf16 v[34:37], v[202:205], v[190:193], v[34:37]
	v_mfma_f32_16x16x32_bf16 v[30:33], v[226:229], v[190:193], v[30:33]
	v_mfma_f32_16x16x32_bf16 v[26:29], v[230:233], v[190:193], v[26:29]
	v_mfma_f32_16x16x32_bf16 v[22:25], v[198:201], v[194:197], v[22:25]
	v_mfma_f32_16x16x32_bf16 v[18:21], v[202:205], v[194:197], v[18:21]
	v_mfma_f32_16x16x32_bf16 v[14:17], v[226:229], v[194:197], v[14:17]
	v_mfma_f32_16x16x32_bf16 v[10:13], v[230:233], v[194:197], v[10:13]
	s_and_b32 s4, s6, 0x1fffffc
	v_add_u32_e32 v139, s7, v153
	s_cmp_lg_u32 s4, 8
	v_or_b32_e32 v138, v139, v151
	s_cselect_b64 s[4:5], -1, 0
	s_movk_i32 s6, 0xe00
	v_lshl_add_u32 v147, v138, 4, v223
	v_mul_lo_u32 v146, v138, s6
	v_or_b32_e32 v140, s9, v155
	s_mov_b64 s[6:7], -1
	s_and_b64 vcc, exec, s[4:5]
	s_cbranch_vccz .LBB0_2204
	s_cmpk_gt_u32 s9, 0xdff
	s_cbranch_scc0 .LBB0_2201
	s_movk_i32 s6, 0xe10
	v_cmp_gt_u32_e32 vcc, s6, v140
	s_and_saveexec_b64 s[6:7], vcc
	s_cbranch_execz .LBB0_2200
	v_readlane_b32 s10, v246, 11
	v_add_u32_e32 v8, v147, v140
	v_readlane_b32 s11, v246, 12
	s_nop 1
	v_lshl_add_u64 v[148:149], v[8:9], 2, s[10:11]
	global_store_dwordx4 v[148:149], v[134:137], off

;     ...
;   for (int it = 0;; it++) {
;     int tile;
;     if (nb == 512) tile = ((it * 8 + (bid & 7)) << 6) + (bid >> 3); else tile = it * nb + bid;
;     tile += tbeg;
;     if (tile >= MTX * ntn || tile >= tend) break;
;     int mt, nt;
;     if (tile < nfull) { const int b_ = tile / band, w_ = tile - b_ * band; nt = w_ >> 3; mt = b_ * 8 + (w_ & 7); }
;     else { const int w_ = tile - nfull; nt = w_ / MREM; mt = (MTX / 8) * 8 + (w_ - nt * MREM); }
;     const int m0 = mt * BM, n0 = nt * 128;
;     f32x4 acc[MI][4];
; #pragma unroll
;     for (int i = 0; i < MI; i++)
; #pragma unroll
;       for (int j = 0; j < 4; j++) acc[i][j] = (f32x4){0.f, 0.f, 0.f, 0.f};
;     ...
;       const bf16_t* ap = A + (size_t)(m0 + lrow) * lda + lsw;
;       const bf16_t* bp = Wt + (size_t)(n0 + lrow) * K + lsw;
;       const size_t a32 = (size_t)32 * lda, b32 = (size_t)32 * K;
.LBB0_2572:
	s_ashr_i32 s4, s2, 31
	s_lshr_b32 s4, s4, 26
	s_add_i32 s4, s2, s4
	s_ashr_i32 s4, s4, 6
	s_lshl_b32 s5, s4, 11
	s_lshl_b32 s4, s4, 10
	s_lshl_b32 s2, s2, 4
	s_sub_i32 s2, s2, s4
	v_mov_b32_e32 v137, 0
	s_or_b32 s17, s5, s15
	s_and_b32 s18, s2, 0xffffff80
	s_andn2_b64 vcc, exec, s[0:1]
	v_mov_b32_e32 v136, v137
	v_mov_b32_e32 v135, v137
	v_mov_b32_e32 v134, v137
	v_mov_b32_e32 v133, v137
	v_mov_b32_e32 v132, v137
	v_mov_b32_e32 v131, v137
	v_mov_b32_e32 v130, v137
	v_mov_b32_e32 v129, v137
	v_mov_b32_e32 v128, v137
	v_mov_b32_e32 v127, v137
	v_mov_b32_e32 v126, v137
	v_mov_b32_e32 v125, v137
	v_mov_b32_e32 v124, v137
	v_mov_b32_e32 v123, v137
	v_mov_b32_e32 v122, v137
	v_mov_b32_e32 v121, v137
	v_mov_b32_e32 v120, v137
	v_mov_b32_e32 v119, v137
	v_mov_b32_e32 v118, v137
	v_mov_b32_e32 v117, v137
	v_mov_b32_e32 v116, v137
	v_mov_b32_e32 v115, v137
	v_mov_b32_e32 v114, v137
	v_mov_b32_e32 v113, v137
	v_mov_b32_e32 v112, v137
	v_mov_b32_e32 v111, v137
	v_mov_b32_e32 v110, v137
	v_mov_b32_e32 v109, v137
	v_mov_b32_e32 v108, v137
	v_mov_b32_e32 v107, v137
	v_mov_b32_e32 v106, v137
	v_mov_b32_e32 v105, v137
	v_mov_b32_e32 v104, v137
	v_mov_b32_e32 v103, v137
	v_mov_b32_e32 v102, v137
	v_mov_b32_e32 v101, v137
	v_mov_b32_e32 v100, v137
	v_mov_b32_e32 v99, v137
	v_mov_b32_e32 v98, v137
	v_mov_b32_e32 v97, v137
	v_mov_b32_e32 v96, v137
	v_mov_b32_e32 v95, v137
	v_mov_b32_e32 v94, v137
	v_mov_b32_e32 v93, v137
	v_mov_b32_e32 v92, v137
	v_mov_b32_e32 v91, v137
	v_mov_b32_e32 v90, v137
	v_mov_b32_e32 v89, v137
	v_mov_b32_e32 v88, v137
	v_mov_b32_e32 v87, v137
	v_mov_b32_e32 v86, v137
	v_mov_b32_e32 v85, v137
	v_mov_b32_e32 v84, v137
	v_mov_b32_e32 v83, v137
	v_mov_b32_e32 v82, v137
	v_mov_b32_e32 v81, v137
	v_mov_b32_e32 v80, v137
	v_mov_b32_e32 v79, v137
	v_mov_b32_e32 v78, v137
	v_mov_b32_e32 v77, v137
	v_mov_b32_e32 v76, v137
	v_mov_b32_e32 v75, v137
	v_mov_b32_e32 v74, v137
	v_mov_b32_e32 v73, v137
	v_mov_b32_e32 v72, v137
	v_mov_b32_e32 v71, v137
	v_mov_b32_e32 v70, v137
	v_mov_b32_e32 v69, v137
	v_mov_b32_e32 v68, v137
	v_mov_b32_e32 v67, v137
	v_mov_b32_e32 v66, v137
	v_mov_b32_e32 v65, v137
	v_mov_b32_e32 v64, v137
	v_mov_b32_e32 v63, v137
	v_mov_b32_e32 v62, v137
	v_mov_b32_e32 v61, v137
	v_mov_b32_e32 v60, v137
	v_mov_b32_e32 v59, v137
	v_mov_b32_e32 v58, v137
	v_mov_b32_e32 v57, v137
	v_mov_b32_e32 v56, v137
	v_mov_b32_e32 v55, v137
	v_mov_b32_e32 v54, v137
	v_mov_b32_e32 v53, v137
	v_mov_b32_e32 v52, v137
	v_mov_b32_e32 v51, v137
	v_mov_b32_e32 v50, v137
	v_mov_b32_e32 v49, v137
	v_mov_b32_e32 v48, v137
	v_mov_b32_e32 v47, v137
	v_mov_b32_e32 v46, v137
	v_mov_b32_e32 v45, v137
	v_mov_b32_e32 v44, v137
	v_mov_b32_e32 v43, v137
	v_mov_b32_e32 v42, v137
	v_mov_b32_e32 v41, v137
	v_mov_b32_e32 v40, v137
	v_mov_b32_e32 v39, v137
	v_mov_b32_e32 v38, v137
	v_mov_b32_e32 v37, v137
	v_mov_b32_e32 v36, v137
	v_mov_b32_e32 v35, v137
	v_mov_b32_e32 v34, v137
	v_mov_b32_e32 v33, v137
	v_mov_b32_e32 v32, v137
	v_mov_b32_e32 v31, v137
	v_mov_b32_e32 v30, v137
	v_mov_b32_e32 v29, v137
	v_mov_b32_e32 v28, v137
	v_mov_b32_e32 v27, v137
	v_mov_b32_e32 v26, v137
	v_mov_b32_e32 v25, v137
	v_mov_b32_e32 v24, v137
	v_mov_b32_e32 v23, v137
	v_mov_b32_e32 v22, v137
	v_mov_b32_e32 v21, v137
	v_mov_b32_e32 v20, v137
	v_mov_b32_e32 v19, v137
	v_mov_b32_e32 v18, v137
	v_mov_b32_e32 v17, v137
	v_mov_b32_e32 v16, v137
	v_mov_b32_e32 v15, v137
	v_mov_b32_e32 v14, v137
	v_mov_b32_e32 v13, v137
	v_mov_b32_e32 v12, v137
	v_mov_b32_e32 v11, v137
	v_mov_b32_e32 v10, v137
	s_cbranch_vccnz .LBB0_2575
	v_add_u32_e32 v8, s17, v150
	v_mad_u64_u32 v[10:11], s[4:5], v8, s28, 0
	v_ashrrev_i32_e32 v12, 31, v8
	v_mov_b32_e32 v8, v11
	v_mad_u64_u32 v[12:13], s[4:5], v12, s28, v[8:9]
	v_mov_b32_e32 v11, v12
	v_add_u32_e32 v8, s18, v150
	v_lshl_add_u64 v[146:147], v[10:11], 1, v[142:143]
	v_mad_u64_u32 v[10:11], s[4:5], v8, s28, 0
	v_ashrrev_i32_e32 v12, 31, v8
	v_mov_b32_e32 v8, v11
	v_mad_u64_u32 v[12:13], s[4:5], v12, s28, v[8:9]
	v_mov_b32_e32 v11, v12
	v_lshl_add_u64 v[148:149], v[10:11], 1, v[144:145]
	v_mov_b32_e32 v10, 0
	s_mov_b32 s2, 0
	s_mov_b32 s19, s12
	v_mov_b32_e32 v11, v10
	v_mov_b32_e32 v12, v10
	v_mov_b32_e32 v13, v10
	v_mov_b32_e32 v14, v10
	v_mov_b32_e32 v15, v10
	v_mov_b32_e32 v16, v10
	v_mov_b32_e32 v17, v10
	v_mov_b32_e32 v18, v10
	v_mov_b32_e32 v19, v10
	v_mov_b32_e32 v20, v10
	v_mov_b32_e32 v21, v10
	v_mov_b32_e32 v22, v10
	v_mov_b32_e32 v23, v10
	v_mov_b32_e32 v24, v10
	v_mov_b32_e32 v25, v10
	v_mov_b32_e32 v26, v10
	v_mov_b32_e32 v27, v10
	v_mov_b32_e32 v28, v10
	v_mov_b32_e32 v29, v10
	v_mov_b32_e32 v30, v10
	v_mov_b32_e32 v31, v10
	v_mov_b32_e32 v32, v10
	v_mov_b32_e32 v33, v10
	v_mov_b32_e32 v34, v10
	v_mov_b32_e32 v35, v10
	v_mov_b32_e32 v36, v10
	v_mov_b32_e32 v37, v10
	v_mov_b32_e32 v38, v10
	v_mov_b32_e32 v39, v10
	v_mov_b32_e32 v40, v10
	v_mov_b32_e32 v41, v10
	v_mov_b32_e32 v42, v10
	v_mov_b32_e32 v43, v10
	v_mov_b32_e32 v44, v10
	v_mov_b32_e32 v45, v10
	v_mov_b32_e32 v46, v10
	v_mov_b32_e32 v47, v10
	v_mov_b32_e32 v48, v10
	v_mov_b32_e32 v49, v10
	v_mov_b32_e32 v50, v10
	v_mov_b32_e32 v51, v10
	v_mov_b32_e32 v52, v10
	v_mov_b32_e32 v53, v10
	v_mov_b32_e32 v54, v10
	v_mov_b32_e32 v55, v10
	v_mov_b32_e32 v56, v10
	v_mov_b32_e32 v57, v10
	v_mov_b32_e32 v58, v10
	v_mov_b32_e32 v59, v10
	v_mov_b32_e32 v60, v10
	v_mov_b32_e32 v61, v10
	v_mov_b32_e32 v62, v10
	v_mov_b32_e32 v63, v10
	v_mov_b32_e32 v64, v10
	v_mov_b32_e32 v65, v10
	v_mov_b32_e32 v66, v10
	v_mov_b32_e32 v67, v10
	v_mov_b32_e32 v68, v10
	v_mov_b32_e32 v69, v10
	v_mov_b32_e32 v70, v10
	v_mov_b32_e32 v71, v10
	v_mov_b32_e32 v72, v10
	v_mov_b32_e32 v73, v10
	v_mov_b32_e32 v74, v10
;     ...
;       const bf16_t* ap = A + (size_t)(m0 + lrow) * lda + lsw;
;       const bf16_t* bp = Wt + (size_t)(n0 + lrow) * K + lsw;
;       const size_t a32 = (size_t)32 * lda, b32 = (size_t)32 * K;
;       typedef __attribute__((address_space(3))) unsigned lds_u32;
;       lds_u32* sbase = (lds_u32*)(smem) + wave * 256;
;       for (int kt = 0; kt < KT; kt++) {
;         {
;           const bf16_t* apx = ap;
;           int kc = kt * 64;
;           if (SHIFT && kc >= 1024) { apx = ap - lda; kc -= 1024; }
; #pragma unroll
;           for (int i = 0; i < 8; i++)
;             __builtin_amdgcn_global_load_lds((const unsigned*)(apx + i * a32 + kc), sbase + i * 1024, 16, 0, 0);
; #pragma unroll
;           for (int i = 0; i < 4; i++)
;             __builtin_amdgcn_global_load_lds((const unsigned*)(bp + i * b32 + kt * 64), sbase + 8192 + i * 1024, 16, 0, 0);
;         }
;         asm volatile("s_waitcnt vmcnt(0)" ::: "memory");
	v_mov_b32_e32 v75, v10
	v_mov_b32_e32 v76, v10
	v_mov_b32_e32 v77, v10
	v_mov_b32_e32 v78, v10
	v_mov_b32_e32 v79, v10
	v_mov_b32_e32 v80, v10
	v_mov_b32_e32 v81, v10
	v_mov_b32_e32 v82, v10
	v_mov_b32_e32 v83, v10
	v_mov_b32_e32 v84, v10
	v_mov_b32_e32 v85, v10
	v_mov_b32_e32 v86, v10
	v_mov_b32_e32 v87, v10
	v_mov_b32_e32 v88, v10
	v_mov_b32_e32 v89, v10
	v_mov_b32_e32 v90, v10
	v_mov_b32_e32 v91, v10
	v_mov_b32_e32 v92, v10
	v_mov_b32_e32 v93, v10
	v_mov_b32_e32 v94, v10
	v_mov_b32_e32 v95, v10
	v_mov_b32_e32 v96, v10
	v_mov_b32_e32 v97, v10
	v_mov_b32_e32 v98, v10
	v_mov_b32_e32 v99, v10
	v_mov_b32_e32 v100, v10
	v_mov_b32_e32 v101, v10
	v_mov_b32_e32 v102, v10
	v_mov_b32_e32 v103, v10
	v_mov_b32_e32 v104, v10
	v_mov_b32_e32 v105, v10
	v_mov_b32_e32 v106, v10
	v_mov_b32_e32 v107, v10
	v_mov_b32_e32 v108, v10
	v_mov_b32_e32 v109, v10
	v_mov_b32_e32 v110, v10
	v_mov_b32_e32 v111, v10
	v_mov_b32_e32 v112, v10
	v_mov_b32_e32 v113, v10
	v_mov_b32_e32 v114, v10
	v_mov_b32_e32 v115, v10
	v_mov_b32_e32 v116, v10
	v_mov_b32_e32 v117, v10
	v_mov_b32_e32 v118, v10
	v_mov_b32_e32 v119, v10
	v_mov_b32_e32 v120, v10
	v_mov_b32_e32 v121, v10
	v_mov_b32_e32 v122, v10
	v_mov_b32_e32 v123, v10
	v_mov_b32_e32 v124, v10
	v_mov_b32_e32 v125, v10
	v_mov_b32_e32 v126, v10
	v_mov_b32_e32 v127, v10
	v_mov_b32_e32 v128, v10
	v_mov_b32_e32 v129, v10
	v_mov_b32_e32 v130, v10
	v_mov_b32_e32 v131, v10
	v_mov_b32_e32 v132, v10
	v_mov_b32_e32 v133, v10
	v_mov_b32_e32 v134, v10
	v_mov_b32_e32 v135, v10
	v_mov_b32_e32 v136, v10
	v_mov_b32_e32 v137, v10
	v_lshrrev_b32_e32 v239, 3, v2
	v_and_b32_e32 v239, 7, v239
	v_lshrrev_b32_e32 v236, 4, v2
	v_xor_b32_e32 v236, v236, v2
	v_and_b32_e32 v236, 7, v236
	v_lshlrev_b32_e32 v236, 4, v236
	s_lshr_b32 s100, s8, 5
	v_mul_lo_u32 v238, v239, s100
	v_add_u32_e32 v238, v238, v236
	v_sub_co_u32_e32 v236, vcc, v146, v238
	s_nop 1
	v_subbrev_co_u32_e32 v237, vcc, 0, v147, vcc
	v_readfirstlane_b32 s32, v151
	v_readfirstlane_b32 s20, v236
	v_readfirstlane_b32 s21, v237
	s_add_u32 s22, s20, s8
	s_addc_u32 s23, s21, s9
	s_add_u32 s24, s22, s8
	s_addc_u32 s25, s23, s9
	s_add_u32 s26, s24, s8
	s_addc_u32 s27, s25, s9
	s_add_u32 s30, s26, s8
	s_addc_u32 s31, s27, s9
	s_add_u32 s48, s30, s8
	s_addc_u32 s49, s31, s9
	s_add_u32 s50, s48, s8
	s_addc_u32 s51, s49, s9
	s_add_u32 s96, s50, s8
	s_addc_u32 s97, s51, s9
	v_mov_b32_e32 v230, v148
	v_mov_b32_e32 v231, v149
	v_lshl_add_u64 v[232:233], v[230:231], 0, s[8:9]
	v_lshl_add_u64 v[234:235], v[232:233], 0, s[8:9]
	v_lshl_add_u64 v[236:237], v[234:235], 0, s[8:9]
	s_mov_b64 s[100:101], 0x80
	s_mov_b32 m0, s32
	s_nop 0
	global_load_lds_dwordx4 v238, s[20:21]
	s_add_u32 m0, s32, 0x1000
	s_nop 0
	global_load_lds_dwordx4 v238, s[22:23]
	s_add_u32 m0, s32, 0x2000
	s_nop 0
	global_load_lds_dwordx4 v238, s[24:25]
	s_add_u32 m0, s32, 0x3000
	s_nop 0
	global_load_lds_dwordx4 v238, s[26:27]
	s_add_u32 m0, s32, 0x4000
	s_nop 0
	global_load_lds_dwordx4 v238, s[30:31]
	s_add_u32 m0, s32, 0x5000
	s_nop 0
	global_load_lds_dwordx4 v238, s[48:49]
	s_add_u32 m0, s32, 0x6000
	s_nop 0
	global_load_lds_dwordx4 v238, s[50:51]
	s_add_u32 m0, s32, 0x7000
	s_nop 0
	global_load_lds_dwordx4 v238, s[96:97]
	s_add_u32 m0, s32, 0x8000
	s_nop 0
	global_load_lds_dwordx4 v[230:231], off
	s_add_u32 m0, s32, 0x9000
	s_nop 0
	global_load_lds_dwordx4 v[232:233], off
	s_add_u32 m0, s32, 0xa000
	s_nop 0
	global_load_lds_dwordx4 v[234:235], off
	s_add_u32 m0, s32, 0xb000
	s_nop 0
	global_load_lds_dwordx4 v[236:237], off
.Lrs_loop:
	s_waitcnt vmcnt(0)
	s_barrier
	v_add_u32_e32 v8, v154, v155
	ds_read_b128 v[166:169], v8
	ds_read_b128 v[170:173], v8 offset:2048
	ds_read_b128 v[174:177], v8 offset:4096
	ds_read_b128 v[178:181], v8 offset:6144
	ds_read_b128 v[182:185], v8 offset:8192
	ds_read_b128 v[186:189], v8 offset:10240
	ds_read_b128 v[190:193], v8 offset:12288
	ds_read_b128 v[138:141], v8 offset:14336
	ds_read_b128 v[194:197], v157 offset:32768
	ds_read_b128 v[198:201], v157 offset:34816
	ds_read_b128 v[202:205], v157 offset:36864
	ds_read_b128 v[226:229], v157 offset:38912
	v_add_u32_e32 v8, v156, v155
	s_waitcnt lgkmcnt(3)
	v_mfma_f32_16x16x32_bf16 v[134:137], v[194:197], v[166:169], v[134:137]
	s_add_i32 s19, s19, -1
	s_add_i32 s2, s2, 64
	s_cmp_eq_u32 s19, 0
	s_waitcnt lgkmcnt(2)
	v_mfma_f32_16x16x32_bf16 v[130:133], v[198:201], v[166:169], v[130:133]
	s_waitcnt lgkmcnt(1)
	v_mfma_f32_16x16x32_bf16 v[126:129], v[202:205], v[166:169], v[126:129]
	s_waitcnt lgkmcnt(0)
	v_mfma_f32_16x16x32_bf16 v[122:125], v[226:229], v[166:169], v[122:125]
	v_mfma_f32_16x16x32_bf16 v[118:121], v[194:197], v[170:173], v[118:121]
	v_mfma_f32_16x16x32_bf16 v[114:117], v[198:201], v[170:173], v[114:117]
	v_mfma_f32_16x16x32_bf16 v[110:113], v[202:205], v[170:173], v[110:113]
	v_mfma_f32_16x16x32_bf16 v[106:109], v[226:229], v[170:173], v[106:109]
	v_mfma_f32_16x16x32_bf16 v[102:105], v[194:197], v[174:177], v[102:105]
	v_mfma_f32_16x16x32_bf16 v[98:101], v[198:201], v[174:177], v[98:101]
	v_mfma_f32_16x16x32_bf16 v[94:97], v[202:205], v[174:177], v[94:97]
	v_mfma_f32_16x16x32_bf16 v[90:93], v[226:229], v[174:177], v[90:93]
	v_mfma_f32_16x16x32_bf16 v[86:89], v[194:197], v[178:181], v[86:89]
	v_mfma_f32_16x16x32_bf16 v[82:85], v[198:201], v[178:181], v[82:85]
	v_mfma_f32_16x16x32_bf16 v[78:81], v[202:205], v[178:181], v[78:81]
	v_mfma_f32_16x16x32_bf16 v[74:77], v[226:229], v[178:181], v[74:77]
	v_mfma_f32_16x16x32_bf16 v[70:73], v[194:197], v[182:185], v[70:73]
	v_mfma_f32_16x16x32_bf16 v[66:69], v[198:201], v[182:185], v[66:69]
	v_mfma_f32_16x16x32_bf16 v[62:65], v[202:205], v[182:185], v[62:65]
	v_mfma_f32_16x16x32_bf16 v[58:61], v[226:229], v[182:185], v[58:61]
	v_mfma_f32_16x16x32_bf16 v[54:57], v[194:197], v[186:189], v[54:57]
	v_mfma_f32_16x16x32_bf16 v[50:53], v[198:201], v[186:189], v[50:53]
	v_mfma_f32_16x16x32_bf16 v[46:49], v[202:205], v[186:189], v[46:49]
	v_mfma_f32_16x16x32_bf16 v[42:45], v[226:229], v[186:189], v[42:45]
	v_mfma_f32_16x16x32_bf16 v[38:41], v[194:197], v[190:193], v[38:41]
	v_mfma_f32_16x16x32_bf16 v[34:37], v[198:201], v[190:193], v[34:37]
	v_mfma_f32_16x16x32_bf16 v[30:33], v[202:205], v[190:193], v[30:33]
	v_mfma_f32_16x16x32_bf16 v[26:29], v[226:229], v[190:193], v[26:29]
	v_mfma_f32_16x16x32_bf16 v[22:25], v[194:197], v[138:141], v[22:25]
	v_mfma_f32_16x16x32_bf16 v[18:21], v[198:201], v[138:141], v[18:21]
	v_mfma_f32_16x16x32_bf16 v[14:17], v[202:205], v[138:141], v[14:17]
	v_mfma_f32_16x16x32_bf16 v[10:13], v[226:229], v[138:141], v[10:13]
	ds_read_b128 v[138:141], v8
	ds_read_b128 v[166:169], v8 offset:2048
	ds_read_b128 v[170:173], v8 offset:4096
	ds_read_b128 v[174:177], v8 offset:6144
	ds_read_b128 v[178:181], v8 offset:8192
	ds_read_b128 v[182:185], v8 offset:10240
	ds_read_b128 v[186:189], v8 offset:12288
	ds_read_b128 v[190:193], v8 offset:14336
	ds_read_b128 v[194:197], v158 offset:32768
	ds_read_b128 v[198:201], v158 offset:34816
	ds_read_b128 v[202:205], v158 offset:36864
	ds_read_b128 v[226:229], v158 offset:38912
	s_waitcnt lgkmcnt(0)
	s_barrier
;     ...
;       for (int kt = 0; kt < KT; kt++) {
;         {
;           const bf16_t* apx = ap;
;           int kc = kt * 64;
;           if (SHIFT && kc >= 1024) { apx = ap - lda; kc -= 1024; }
; #pragma unroll
;           for (int i = 0; i < 8; i++)
;             __builtin_amdgcn_global_load_lds((const unsigned*)(apx + i * a32 + kc), sbase + i * 1024, 16, 0, 0);
; #pragma unroll
;           for (int i = 0; i < 4; i++)
;             __builtin_amdgcn_global_load_lds((const unsigned*)(bp + i * b32 + kt * 64), sbase + 8192 + i * 1024, 16, 0, 0);
;         }
;         asm volatile("s_waitcnt vmcnt(0)" ::: "memory");
;         __syncthreads();
; #pragma unroll
;         for (int kk = 0; kk < 2; kk++) {
;           bf16x8 af[MI], bfr[4];
;           const int csw = (((kk * 4 + fq) ^ fsw) << 3);
; #pragma unroll
;           for (int mi = 0; mi < MI; mi++) af[mi] = *(const bf16x8*)(smem + (wm * 128 + mi * 16 + fr) * 64 + csw);
; #pragma unroll
;           for (int ni = 0; ni < 4; ni++) bfr[ni] = *(const bf16x8*)(smem + 16384 + (wn * 64 + ni * 16 + fr) * 64 + csw);
; #pragma unroll
;           for (int mi = 0; mi < MI; mi++)
; #pragma unroll
;             for (int ni = 0; ni < 4; ni++)
;               acc[mi][ni] = __builtin_amdgcn_mfma_f32_16x16x32_bf16(bfr[ni], af[mi], acc[mi][ni], 0, 0, 0);
	s_cmp_eq_u32 s19, 0
	s_cbranch_scc1 .Lrs_last
	v_add_u32_e32 v238, 0x80, v238
	v_lshl_add_u64 v[230:231], v[230:231], 0, s[100:101]
	v_lshl_add_u64 v[232:233], v[232:233], 0, s[100:101]
	v_lshl_add_u64 v[234:235], v[234:235], 0, s[100:101]
	v_lshl_add_u64 v[236:237], v[236:237], 0, s[100:101]
	v_mfma_f32_16x16x32_bf16 v[134:137], v[194:197], v[138:141], v[134:137]
	v_mfma_f32_16x16x32_bf16 v[130:133], v[198:201], v[138:141], v[130:133]
	v_mfma_f32_16x16x32_bf16 v[126:129], v[202:205], v[138:141], v[126:129]
	v_mfma_f32_16x16x32_bf16 v[122:125], v[226:229], v[138:141], v[122:125]
	v_mfma_f32_16x16x32_bf16 v[118:121], v[194:197], v[166:169], v[118:121]
	v_mfma_f32_16x16x32_bf16 v[114:117], v[198:201], v[166:169], v[114:117]
	s_mov_b32 m0, s32
	v_mfma_f32_16x16x32_bf16 v[110:113], v[202:205], v[166:169], v[110:113]
	global_load_lds_dwordx4 v238, s[20:21]
	v_mfma_f32_16x16x32_bf16 v[106:109], v[226:229], v[166:169], v[106:109]
	s_add_u32 m0, s32, 0x1000
	v_mfma_f32_16x16x32_bf16 v[102:105], v[194:197], v[170:173], v[102:105]
	global_load_lds_dwordx4 v238, s[22:23]
	v_mfma_f32_16x16x32_bf16 v[98:101], v[198:201], v[170:173], v[98:101]
	s_add_u32 m0, s32, 0x2000
	v_mfma_f32_16x16x32_bf16 v[94:97], v[202:205], v[170:173], v[94:97]
	global_load_lds_dwordx4 v238, s[24:25]
	v_mfma_f32_16x16x32_bf16 v[90:93], v[226:229], v[170:173], v[90:93]
	s_add_u32 m0, s32, 0x3000
	v_mfma_f32_16x16x32_bf16 v[86:89], v[194:197], v[174:177], v[86:89]
	global_load_lds_dwordx4 v238, s[26:27]
	v_mfma_f32_16x16x32_bf16 v[82:85], v[198:201], v[174:177], v[82:85]
	s_add_u32 m0, s32, 0x4000
	v_mfma_f32_16x16x32_bf16 v[78:81], v[202:205], v[174:177], v[78:81]
	global_load_lds_dwordx4 v238, s[30:31]
	v_mfma_f32_16x16x32_bf16 v[74:77], v[226:229], v[174:177], v[74:77]
	s_add_u32 m0, s32, 0x5000
	v_mfma_f32_16x16x32_bf16 v[70:73], v[194:197], v[178:181], v[70:73]
	global_load_lds_dwordx4 v238, s[48:49]
	v_mfma_f32_16x16x32_bf16 v[66:69], v[198:201], v[178:181], v[66:69]
	s_add_u32 m0, s32, 0x6000
	v_mfma_f32_16x16x32_bf16 v[62:65], v[202:205], v[178:181], v[62:65]
	global_load_lds_dwordx4 v238, s[50:51]
	v_mfma_f32_16x16x32_bf16 v[58:61], v[226:229], v[178:181], v[58:61]
	s_add_u32 m0, s32, 0x7000
	v_mfma_f32_16x16x32_bf16 v[54:57], v[194:197], v[182:185], v[54:57]
	global_load_lds_dwordx4 v238, s[96:97]
	v_mfma_f32_16x16x32_bf16 v[50:53], v[198:201], v[182:185], v[50:53]
	s_add_u32 m0, s32, 0x8000
	v_mfma_f32_16x16x32_bf16 v[46:49], v[202:205], v[182:185], v[46:49]
	global_load_lds_dwordx4 v[230:231], off
	v_mfma_f32_16x16x32_bf16 v[42:45], v[226:229], v[182:185], v[42:45]
	s_add_u32 m0, s32, 0x9000
	v_mfma_f32_16x16x32_bf16 v[38:41], v[194:197], v[186:189], v[38:41]
	global_load_lds_dwordx4 v[232:233], off
	v_mfma_f32_16x16x32_bf16 v[34:37], v[198:201], v[186:189], v[34:37]
	s_add_u32 m0, s32, 0xa000
	v_mfma_f32_16x16x32_bf16 v[30:33], v[202:205], v[186:189], v[30:33]
	global_load_lds_dwordx4 v[234:235], off
	v_mfma_f32_16x16x32_bf16 v[26:29], v[226:229], v[186:189], v[26:29]
	s_add_u32 m0, s32, 0xb000
	v_mfma_f32_16x16x32_bf16 v[22:25], v[194:197], v[190:193], v[22:25]
	global_load_lds_dwordx4 v[236:237], off
	v_mfma_f32_16x16x32_bf16 v[18:21], v[198:201], v[190:193], v[18:21]
	v_mfma_f32_16x16x32_bf16 v[14:17], v[202:205], v[190:193], v[14:17]
	v_mfma_f32_16x16x32_bf16 v[10:13], v[226:229], v[190:193], v[10:13]
	s_branch .Lrs_loop
.Lrs_last:
	v_mfma_f32_16x16x32_bf16 v[134:137], v[194:197], v[138:141], v[134:137]
	v_mfma_f32_16x16x32_bf16 v[130:133], v[198:201], v[138:141], v[130:133]
	v_mfma_f32_16x16x32_bf16 v[126:129], v[202:205], v[138:141], v[126:129]
	v_mfma_f32_16x16x32_bf16 v[122:125], v[226:229], v[138:141], v[122:125]
	v_mfma_f32_16x16x32_bf16 v[118:121], v[194:197], v[166:169], v[118:121]
	v_mfma_f32_16x16x32_bf16 v[114:117], v[198:201], v[166:169], v[114:117]
	v_mfma_f32_16x16x32_bf16 v[110:113], v[202:205], v[166:169], v[110:113]
	v_mfma_f32_16x16x32_bf16 v[106:109], v[226:229], v[166:169], v[106:109]
	v_mfma_f32_16x16x32_bf16 v[102:105], v[194:197], v[170:173], v[102:105]
	v_mfma_f32_16x16x32_bf16 v[98:101], v[198:201], v[170:173], v[98:101]
	v_mfma_f32_16x16x32_bf16 v[94:97], v[202:205], v[170:173], v[94:97]
	v_mfma_f32_16x16x32_bf16 v[90:93], v[226:229], v[170:173], v[90:93]
	v_mfma_f32_16x16x32_bf16 v[86:89], v[194:197], v[174:177], v[86:89]
	v_mfma_f32_16x16x32_bf16 v[82:85], v[198:201], v[174:177], v[82:85]
	v_mfma_f32_16x16x32_bf16 v[78:81], v[202:205], v[174:177], v[78:81]
	v_mfma_f32_16x16x32_bf16 v[74:77], v[226:229], v[174:177], v[74:77]
	v_mfma_f32_16x16x32_bf16 v[70:73], v[194:197], v[178:181], v[70:73]
	v_mfma_f32_16x16x32_bf16 v[66:69], v[198:201], v[178:181], v[66:69]
	v_mfma_f32_16x16x32_bf16 v[62:65], v[202:205], v[178:181], v[62:65]
	v_mfma_f32_16x16x32_bf16 v[58:61], v[226:229], v[178:181], v[58:61]
	v_mfma_f32_16x16x32_bf16 v[54:57], v[194:197], v[182:185], v[54:57]
	v_mfma_f32_16x16x32_bf16 v[50:53], v[198:201], v[182:185], v[50:53]
	v_mfma_f32_16x16x32_bf16 v[46:49], v[202:205], v[182:185], v[46:49]
	v_mfma_f32_16x16x32_bf16 v[42:45], v[226:229], v[182:185], v[42:45]
	v_mfma_f32_16x16x32_bf16 v[38:41], v[194:197], v[186:189], v[38:41]
	v_mfma_f32_16x16x32_bf16 v[34:37], v[198:201], v[186:189], v[34:37]
	v_mfma_f32_16x16x32_bf16 v[30:33], v[202:205], v[186:189], v[30:33]
	v_mfma_f32_16x16x32_bf16 v[26:29], v[226:229], v[186:189], v[26:29]
	v_mfma_f32_16x16x32_bf16 v[22:25], v[194:197], v[190:193], v[22:25]
	v_mfma_f32_16x16x32_bf16 v[18:21], v[198:201], v[190:193], v[18:21]
	v_mfma_f32_16x16x32_bf16 v[14:17], v[202:205], v[190:193], v[14:17]
	v_mfma_f32_16x16x32_bf16 v[10:13], v[226:229], v[190:193], v[10:13]

; __global__ void __launch_bounds__(256, 2) mega_kernel(Params p) {
;   __shared__ __attribute__((aligned(16))) char smraw[LDS_BYTES];
	.amdhsa_kernel _Z11mega_kernel6Params
		.amdhsa_group_segment_fixed_size 65536
		.amdhsa_private_segment_fixed_size 0
		.amdhsa_kernarg_size 528
		.amdhsa_user_sgpr_count 2
		.amdhsa_user_sgpr_dispatch_ptr 0
		.amdhsa_user_sgpr_queue_ptr 0
		.amdhsa_user_sgpr_kernarg_segment_ptr 1
		.amdhsa_user_sgpr_dispatch_id 0
		.amdhsa_user_sgpr_kernarg_preload_length 0
		.amdhsa_user_sgpr_kernarg_preload_offset 0
		.amdhsa_user_sgpr_private_segment_size 0
		.amdhsa_uses_dynamic_stack 0
		.amdhsa_enable_private_segment 0
		.amdhsa_system_sgpr_workgroup_id_x 1
		.amdhsa_system_sgpr_workgroup_id_y 0
		.amdhsa_system_sgpr_workgroup_id_z 0
		.amdhsa_system_sgpr_workgroup_info 0
		.amdhsa_system_vgpr_workitem_id 2
		.amdhsa_next_free_vgpr 248
		.amdhsa_next_free_sgpr 102
		.amdhsa_accum_offset 248
		.amdhsa_reserve_vcc 1
		.amdhsa_float_round_mode_32 0
		.amdhsa_float_round_mode_16_64 0
		.amdhsa_float_denorm_mode_32 3
		.amdhsa_float_denorm_mode_16_64 3
		.amdhsa_dx10_clamp 1
		.amdhsa_ieee_mode 1
		.amdhsa_fp16_overflow 0
		.amdhsa_tg_split 0
		.amdhsa_exception_fp_ieee_invalid_op 0
		.amdhsa_exception_fp_denorm_src 0
		.amdhsa_exception_fp_ieee_div_zero 0
		.amdhsa_exception_fp_ieee_overflow 0
		.amdhsa_exception_fp_ieee_underflow 0
		.amdhsa_exception_fp_ieee_inexact 0
		.amdhsa_exception_int_div_zero 0
	.end_amdhsa_kernel

; __global__ void __launch_bounds__(256, 2) mega_kernel(Params p) {
;   __shared__ __attribute__((aligned(16))) char smraw[LDS_BYTES];
amdhsa.kernels:
  - .agpr_count:     0
    .args:
      - .offset:         0
        .size:           272
        .value_kind:     by_value
      - .offset:         272
        .size:           4
        .value_kind:     hidden_block_count_x
      - .offset:         276
        .size:           4
        .value_kind:     hidden_block_count_y
      - .offset:         280
        .size:           4
        .value_kind:     hidden_block_count_z
      - .offset:         284
        .size:           2
        .value_kind:     hidden_group_size_x
      - .offset:         286
        .size:           2
        .value_kind:     hidden_group_size_y
      - .offset:         288
        .size:           2
        .value_kind:     hidden_group_size_z
      - .offset:         290
        .size:           2
        .value_kind:     hidden_remainder_x
      - .offset:         292
        .size:           2
        .value_kind:     hidden_remainder_y
      - .offset:         294
        .size:           2
        .value_kind:     hidden_remainder_z
      - .offset:         312
        .size:           8
        .value_kind:     hidden_global_offset_x
      - .offset:         320
        .size:           8
        .value_kind:     hidden_global_offset_y
      - .offset:         328
        .size:           8
        .value_kind:     hidden_global_offset_z
      - .offset:         336
        .size:           2
        .value_kind:     hidden_grid_dims
      - .offset:         360
        .size:           8
        .value_kind:     hidden_multigrid_sync_arg
    .group_segment_fixed_size: 65536
    .kernarg_segment_align: 8
    .kernarg_segment_size: 528
    .language:       OpenCL C
    .language_version:
      - 2
      - 0
    .max_flat_workgroup_size: 256
    .name:           _Z11mega_kernel6Params
    .private_segment_fixed_size: 0
    .sgpr_count:     108
    .sgpr_spill_count: 478
    .symbol:         _Z11mega_kernel6Params.kd
    .uniform_work_group_size: 1
    .uses_dynamic_stack: false
    .vgpr_count:     248
    .vgpr_spill_count: 0
    .wavefront_size: 64
